# v32 + WO/DOWN residual epilogue: first four x loads (row A0) prefetched before the K-loop into registers the K-loop does not use; code placement unchanged
# baseline (speedup 1.0000x reference)
.LBB0_999:
	s_add_i32 m0, s13, 0x18000
	v_lshl_add_u64 v[2:3], v[2:3], 0, s[88:89]
	s_waitcnt vmcnt(2)
	s_barrier
	global_load_lds_dwordx4 v[2:3], off
	v_lshl_add_u64 v[2:3], v[4:5], 0, s[88:89]
	s_add_i32 m0, s13, 0x1a000
	s_add_i32 s52, s13, 0x8000
	global_load_lds_dwordx4 v[2:3], off
	v_lshl_add_u64 v[2:3], v[10:11], 0, s[88:89]
	s_mov_b32 m0, s52
	s_add_i32 s53, s13, 0xa000
	global_load_lds_dwordx4 v[2:3], off
	v_lshl_add_u64 v[2:3], v[12:13], 0, s[88:89]
	s_mov_b32 m0, s53
	v_bfe_u32 v20, v240, 4, 2
	global_load_lds_dwordx4 v[2:3], off
	s_add_i32 m0, s13, 0x1c000
	v_lshl_add_u64 v[2:3], v[6:7], 0, s[88:89]
	global_load_lds_dwordx4 v[2:3], off
	v_lshl_add_u64 v[2:3], v[8:9], 0, s[88:89]
	s_add_i32 m0, s13, 0x1e000
	v_and_b32_e32 v21, 15, v240
	global_load_lds_dwordx4 v[2:3], off
	v_lshlrev_b32_e32 v22, 4, v20
	v_lshl_or_b32 v144, s28, 6, v21
	v_lshl_or_b32 v21, v21, 6, v22
	v_lshlrev_b32_e32 v22, 2, v240
	s_sext_i32_i16 s63, s16
	s_lshl_b32 s16, s28, 13
	v_and_b32_e32 v22, 32, v22
	v_bitop3_b32 v23, v21, s16, v22 bitop3:0xde
	s_lshl_b32 s16, s17, 5
	v_add_u32_e32 v2, v16, v14
	s_lshr_b32 s51, s92, 6
	s_and_b32 s16, s16, 0x60
	v_add_lshl_u32 v2, v2, v15, 1
	v_mov_b32_e32 v3, v1
	s_xor_b64 s[6:7], s[6:7], -1
	s_lshl_b32 s17, s16, 7
	s_waitcnt vmcnt(6)
	s_add_i32 s55, s51, -2
	v_lshl_add_u64 v[136:137], s[18:19], 0, v[2:3]
	v_add_u32_e32 v2, v19, v17
	s_cmpk_lt_u32 s1, 0x100
	v_add_lshl_u32 v2, v2, v18, 1
	v_bitop3_b32 v145, s17, v21, v22 bitop3:0xf6
	s_cselect_b64 s[28:29], -1, 0
	s_mov_b32 s1, s56
	v_lshl_or_b32 v146, v20, 2, s16
	v_lshl_add_u64 v[138:139], s[18:19], 0, v[2:3]
	s_mov_b32 s19, 0
	v_add_u32_e32 v147, 0, v23
	s_nop 0
	s_nop 0
	s_nop 0
	s_nop 0
	s_nop 0
	s_nop 0
	s_nop 0
	s_load_dwordx2 vcc, s[48:49], 0x140
	v_lshl_add_u32 v228, s59, 8, v144
	v_lshl_or_b32 v230, s63, 8, v146
	v_ashrrev_i32_e32 v229, 31, v228
	v_ashrrev_i32_e32 v231, 31, v230
	v_lshlrev_b64 v[228:229], 12, v[228:229]
	v_lshlrev_b64 v[230:231], 2, v[230:231]
	s_waitcnt lgkmcnt(0)
	v_lshl_add_u64 v[228:229], vcc, 0, v[228:229]
	v_lshl_add_u64 v[250:251], v[228:229], 0, v[230:231]
	global_load_dwordx4 v[228:231], v[250:251], off
	global_load_dwordx4 v[232:235], v[250:251], off offset:64
	global_load_dwordx4 v[242:245], v[250:251], off offset:512
	global_load_dwordx4 v[246:249], v[250:251], off offset:576
	s_barrier
	s_branch .LBB0_1002

.LBB0_1013:
	s_cmp_lt_i32 s59, 40
	s_load_dwordx4 s[36:39], s[48:49], 0x140
	s_cselect_b32 s16, s76, 0x3000
	s_cmp_gt_i32 s59, 31
	s_cselect_b32 s16, s16, 0
	v_lshl_add_u32 v152, s59, 8, v144
	s_lshl_b32 s16, s16, 2
	v_lshl_or_b32 v130, s63, 8, v146
	v_ashrrev_i32_e32 v153, 31, v152
	s_add_u32 s16, s14, s16
	v_ashrrev_i32_e32 v131, 31, v130
	v_lshlrev_b64 v[142:143], 12, v[152:153]
	s_addc_u32 s17, s15, 0
	v_lshlrev_b64 v[154:155], 2, v[130:131]
	s_waitcnt lgkmcnt(0)
	v_lshl_add_u64 v[142:143], s[36:37], 0, v[142:143]
	v_lshl_add_u64 v[140:141], s[16:17], 0, v[154:155]
	v_lshl_add_u64 v[142:143], v[142:143], 0, v[154:155]
	global_load_dwordx4 v[130:133], v[140:141], off
	global_load_dwordx4 v[148:151], v[140:141], off offset:64
	global_load_dwordx4 v[152:155], v[140:141], off offset:512
	global_load_dwordx4 v[170:173], v[140:141], off offset:576
	s_nop 0
	s_nop 0
	s_nop 0
	s_nop 0
	s_nop 0
	s_cmp_eq_u32 s19, 1
	s_cbranch_scc1 .Lmy_er_usepf
	global_load_dwordx4 v[174:177], v[142:143], off
	global_load_dwordx4 v[178:181], v[142:143], off offset:64
	global_load_dwordx4 v[182:185], v[142:143], off offset:512
	global_load_dwordx4 v[186:189], v[142:143], off offset:576
	s_branch .Lmy_er_pfdone
.Lmy_er_usepf:
	v_mov_b64_e32 v[174:175], v[228:229]
	v_mov_b64_e32 v[176:177], v[230:231]
	v_mov_b64_e32 v[178:179], v[232:233]
	v_mov_b64_e32 v[180:181], v[234:235]
	v_mov_b64_e32 v[182:183], v[242:243]
	v_mov_b64_e32 v[184:185], v[244:245]
	v_mov_b64_e32 v[186:187], v[246:247]
	v_mov_b64_e32 v[188:189], v[248:249]
.Lmy_er_pfdone:
	s_mov_b64 s[16:17], 0x10000
	v_lshl_add_u64 v[156:157], v[142:143], 0, s[16:17]
	global_load_dwordx4 v[196:199], v[156:157], off
	global_load_dwordx4 v[200:203], v[156:157], off offset:64
	global_load_dwordx4 v[204:207], v[156:157], off offset:512
	global_load_dwordx4 v[218:221], v[156:157], off offset:576
	s_mov_b64 s[16:17], 0x20000
	v_lshl_add_u64 v[158:159], v[142:143], 0, s[16:17]
	global_load_dwordx4 v[222:225], v[158:159], off
	s_mov_b64 s[16:17], 0x30000
	v_lshl_add_u64 v[160:161], v[142:143], 0, s[16:17]
	s_mov_b64 s[16:17], 0x80000
	v_lshl_add_u64 v[162:163], v[142:143], 0, s[16:17]
	s_mov_b64 s[16:17], 0x90000
	v_lshl_add_u64 v[164:165], v[142:143], 0, s[16:17]
	s_mov_b64 s[16:17], 0xa0000
	v_lshl_add_u64 v[166:167], v[142:143], 0, s[16:17]
	s_mov_b64 s[16:17], 0xb0000
	v_lshl_add_u64 v[168:169], v[142:143], 0, s[16:17]
	s_mov_b64 s[36:37], -1
	s_waitcnt vmcnt(8)
	v_pk_fma_f32 v[128:129], v[128:129], v[132:133], v[176:177]
	v_pk_fma_f32 v[126:127], v[126:127], v[130:131], v[174:175]
	global_store_dwordx4 v[142:143], v[126:129], off
	global_load_dwordx4 v[174:177], v[158:159], off offset:64
	s_waitcnt vmcnt(9)
	v_pk_fma_f32 v[96:97], v[96:97], v[150:151], v[180:181]
	v_pk_fma_f32 v[94:95], v[94:95], v[148:149], v[178:179]
	global_store_dwordx4 v[142:143], v[94:97], off offset:64
	global_load_dwordx4 v[178:181], v[158:159], off offset:512
	s_waitcnt vmcnt(10)
	v_pk_fma_f32 v[64:65], v[64:65], v[154:155], v[184:185]
	v_pk_fma_f32 v[62:63], v[62:63], v[152:153], v[182:183]
	global_store_dwordx4 v[142:143], v[62:65], off offset:512
	global_load_dwordx4 v[182:185], v[158:159], off offset:576
	s_waitcnt vmcnt(11)
	v_pk_fma_f32 v[32:33], v[32:33], v[172:173], v[188:189]
	v_pk_fma_f32 v[30:31], v[30:31], v[170:171], v[186:187]
	global_store_dwordx4 v[142:143], v[30:33], off offset:576
	global_load_dwordx4 v[186:189], v[160:161], off
	s_waitcnt vmcnt(12)
	v_pk_fma_f32 v[124:125], v[124:125], v[132:133], v[198:199]
	v_pk_fma_f32 v[122:123], v[122:123], v[130:131], v[196:197]
	global_store_dwordx4 v[156:157], v[122:125], off
	global_load_dwordx4 v[196:199], v[160:161], off offset:64
	s_waitcnt vmcnt(13)
	v_pk_fma_f32 v[92:93], v[92:93], v[150:151], v[202:203]
	v_pk_fma_f32 v[90:91], v[90:91], v[148:149], v[200:201]
	global_store_dwordx4 v[156:157], v[90:93], off offset:64
	global_load_dwordx4 v[200:203], v[160:161], off offset:512
	s_waitcnt vmcnt(14)
	v_pk_fma_f32 v[60:61], v[60:61], v[154:155], v[206:207]
	v_pk_fma_f32 v[58:59], v[58:59], v[152:153], v[204:205]
	global_store_dwordx4 v[156:157], v[58:61], off offset:512
	global_load_dwordx4 v[204:207], v[160:161], off offset:576
	s_waitcnt vmcnt(15)
	v_pk_fma_f32 v[28:29], v[28:29], v[172:173], v[220:221]
	v_pk_fma_f32 v[26:27], v[26:27], v[170:171], v[218:219]
	global_store_dwordx4 v[156:157], v[26:29], off offset:576
	global_load_dwordx4 v[218:221], v[162:163], off
	s_waitcnt vmcnt(16)
	v_pk_fma_f32 v[120:121], v[120:121], v[132:133], v[224:225]
	v_pk_fma_f32 v[118:119], v[118:119], v[130:131], v[222:223]
	global_store_dwordx4 v[158:159], v[118:121], off
	global_load_dwordx4 v[222:225], v[162:163], off offset:64
	s_waitcnt vmcnt(16)
	v_pk_fma_f32 v[88:89], v[88:89], v[150:151], v[176:177]
	v_pk_fma_f32 v[86:87], v[86:87], v[148:149], v[174:175]
	global_store_dwordx4 v[158:159], v[86:89], off offset:64
	global_load_dwordx4 v[174:177], v[162:163], off offset:512
	s_waitcnt vmcnt(16)
	v_pk_fma_f32 v[56:57], v[56:57], v[154:155], v[180:181]
	v_pk_fma_f32 v[54:55], v[54:55], v[152:153], v[178:179]
	global_store_dwordx4 v[158:159], v[54:57], off offset:512
	global_load_dwordx4 v[178:181], v[162:163], off offset:576
	s_waitcnt vmcnt(16)
	v_pk_fma_f32 v[24:25], v[24:25], v[172:173], v[184:185]
	v_pk_fma_f32 v[22:23], v[22:23], v[170:171], v[182:183]
	global_store_dwordx4 v[158:159], v[22:25], off offset:576
	global_load_dwordx4 v[182:185], v[164:165], off
	s_waitcnt vmcnt(16)
	v_pk_fma_f32 v[116:117], v[116:117], v[132:133], v[188:189]
	v_pk_fma_f32 v[114:115], v[114:115], v[130:131], v[186:187]
	global_store_dwordx4 v[160:161], v[114:117], off
	global_load_dwordx4 v[186:189], v[164:165], off offset:64
	s_waitcnt vmcnt(16)
	v_pk_fma_f32 v[84:85], v[84:85], v[150:151], v[198:199]
	v_pk_fma_f32 v[82:83], v[82:83], v[148:149], v[196:197]
	global_store_dwordx4 v[160:161], v[82:85], off offset:64
	global_load_dwordx4 v[196:199], v[164:165], off offset:512
	s_waitcnt vmcnt(16)
	v_pk_fma_f32 v[52:53], v[52:53], v[154:155], v[202:203]
	v_pk_fma_f32 v[50:51], v[50:51], v[152:153], v[200:201]
	global_store_dwordx4 v[160:161], v[50:53], off offset:512
	global_load_dwordx4 v[200:203], v[164:165], off offset:576
	s_waitcnt vmcnt(16)
	v_pk_fma_f32 v[20:21], v[20:21], v[172:173], v[206:207]
	v_pk_fma_f32 v[18:19], v[18:19], v[170:171], v[204:205]
	global_store_dwordx4 v[160:161], v[18:21], off offset:576
	global_load_dwordx4 v[204:207], v[166:167], off
	s_waitcnt vmcnt(16)
	v_pk_fma_f32 v[112:113], v[112:113], v[132:133], v[220:221]
	v_pk_fma_f32 v[110:111], v[110:111], v[130:131], v[218:219]
	global_store_dwordx4 v[162:163], v[110:113], off
	global_load_dwordx4 v[218:221], v[166:167], off offset:64
	s_waitcnt vmcnt(16)
	v_pk_fma_f32 v[80:81], v[80:81], v[150:151], v[224:225]
	v_pk_fma_f32 v[78:79], v[78:79], v[148:149], v[222:223]
	global_store_dwordx4 v[162:163], v[78:81], off offset:64
	global_load_dwordx4 v[222:225], v[166:167], off offset:512
	s_waitcnt vmcnt(16)
	v_pk_fma_f32 v[48:49], v[48:49], v[154:155], v[176:177]
	v_pk_fma_f32 v[46:47], v[46:47], v[152:153], v[174:175]
	global_store_dwordx4 v[162:163], v[46:49], off offset:512
	global_load_dwordx4 v[174:177], v[166:167], off offset:576
	s_waitcnt vmcnt(16)
	v_pk_fma_f32 v[16:17], v[16:17], v[172:173], v[180:181]
	v_pk_fma_f32 v[14:15], v[14:15], v[170:171], v[178:179]
	global_store_dwordx4 v[162:163], v[14:17], off offset:576
	global_load_dwordx4 v[178:181], v[168:169], off
	s_waitcnt vmcnt(16)
	v_pk_fma_f32 v[108:109], v[108:109], v[132:133], v[184:185]
	v_pk_fma_f32 v[106:107], v[106:107], v[130:131], v[182:183]
	global_store_dwordx4 v[164:165], v[106:109], off
	global_load_dwordx4 v[182:185], v[168:169], off offset:64
	s_waitcnt vmcnt(16)
	v_pk_fma_f32 v[76:77], v[76:77], v[150:151], v[188:189]
	v_pk_fma_f32 v[74:75], v[74:75], v[148:149], v[186:187]
	global_store_dwordx4 v[164:165], v[74:77], off offset:64
	global_load_dwordx4 v[186:189], v[168:169], off offset:512
	s_waitcnt vmcnt(16)
	v_pk_fma_f32 v[44:45], v[44:45], v[154:155], v[198:199]
	v_pk_fma_f32 v[42:43], v[42:43], v[152:153], v[196:197]
	global_store_dwordx4 v[164:165], v[42:45], off offset:512
	global_load_dwordx4 v[196:199], v[168:169], off offset:576
	s_waitcnt vmcnt(16)
	v_pk_fma_f32 v[12:13], v[12:13], v[172:173], v[202:203]
	v_pk_fma_f32 v[10:11], v[10:11], v[170:171], v[200:201]
	global_store_dwordx4 v[164:165], v[10:13], off offset:576
	s_waitcnt vmcnt(15)
	v_pk_fma_f32 v[104:105], v[104:105], v[132:133], v[206:207]
	v_pk_fma_f32 v[102:103], v[102:103], v[130:131], v[204:205]
	global_store_dwordx4 v[166:167], v[102:105], off
	s_waitcnt vmcnt(14)
	v_pk_fma_f32 v[72:73], v[72:73], v[150:151], v[220:221]
	v_pk_fma_f32 v[70:71], v[70:71], v[148:149], v[218:219]
	global_store_dwordx4 v[166:167], v[70:73], off offset:64
	s_waitcnt vmcnt(13)
	v_pk_fma_f32 v[40:41], v[40:41], v[154:155], v[224:225]
	v_pk_fma_f32 v[38:39], v[38:39], v[152:153], v[222:223]
	global_store_dwordx4 v[166:167], v[38:41], off offset:512
	s_waitcnt vmcnt(12)
	v_pk_fma_f32 v[8:9], v[8:9], v[172:173], v[176:177]
	v_pk_fma_f32 v[6:7], v[6:7], v[170:171], v[174:175]
	global_store_dwordx4 v[166:167], v[6:9], off offset:576
	s_waitcnt vmcnt(11)
	v_pk_fma_f32 v[100:101], v[100:101], v[132:133], v[180:181]
	v_pk_fma_f32 v[98:99], v[98:99], v[130:131], v[178:179]
	global_store_dwordx4 v[168:169], v[98:101], off
	s_waitcnt vmcnt(10)
	v_pk_fma_f32 v[68:69], v[68:69], v[150:151], v[184:185]
	v_pk_fma_f32 v[66:67], v[66:67], v[148:149], v[182:183]
	global_store_dwordx4 v[168:169], v[66:69], off offset:64
	s_waitcnt vmcnt(9)
	v_pk_fma_f32 v[36:37], v[36:37], v[154:155], v[188:189]
	v_pk_fma_f32 v[34:35], v[34:35], v[152:153], v[186:187]
	global_store_dwordx4 v[168:169], v[34:37], off offset:512
	s_waitcnt vmcnt(8)
	v_pk_fma_f32 v[4:5], v[4:5], v[172:173], v[198:199]
	v_pk_fma_f32 v[2:3], v[2:3], v[170:171], v[196:197]
	global_store_dwordx4 v[168:169], v[2:5], off offset:576
	s_and_b64 vcc, exec, s[40:41]
	s_cbranch_vccnz .LBB0_1001
	s_andn2_b64 vcc, exec, s[26:27]
	s_cbranch_vccnz .LBB0_1000
	s_barrier
	s_branch .LBB0_1000
